# GDN S3: diagonal-block T'/T'' writes use one v_cvt_pk_bf16_f32 per (T',T'') pair instead of two bit-trick roundings; T12 zero block written with ds_write_b128
# speedup vs baseline: 1.0050x; 1.0050x over previous
; #define LAS __attribute__((address_space(3)))
; DI unsigned pk2(float lo, float hi) { return f2bf(lo) | (f2bf(hi) << 16); }
; DI void gdn_unit(const Params& P, bf16_t* proj, const float* gb, int b, int h, LAS unsigned char* lds) {
;     ...
;         if (wave == 0) {
;             const int blk = lane >> 5, cl = lane & 31;
;             LAS unsigned char* Lbytes = lds + L_OFF;
;             LAS unsigned char* L21b = (LAS unsigned char*)part;
;             {
;                 const int r = lane >> 1, hh = lane & 1;
;                 f32x4 x[4];
; #pragma unroll
;                 for (int q = 0; q < 4; ++q) x[q] = *(const LAS f32x4*)(Lm + (32 + r) * 64 + hh * 16 + q * 4);
;                 u32x4 w0, w1;
;                 w0.x = pk2(x[0][0], x[0][1]); w0.y = pk2(x[0][2], x[0][3]); w0.z = pk2(x[1][0], x[1][1]); w0.w = pk2(x[1][2], x[1][3]);
;                 w1.x = pk2(x[2][0], x[2][1]); w1.y = pk2(x[2][2], x[2][3]); w1.z = pk2(x[3][0], x[3][1]); w1.w = pk2(x[3][2], x[3][3]);
;                 *(LAS u32x4*)(L21b + r * 64 + hh * 32) = w0; *(LAS u32x4*)(L21b + r * 64 + hh * 32 + 16) = w1;
;             }
;             const LAS float* Lblk = Lm + blk * (32 * 64 + 32);
;             float Tc[32];
; #pragma unroll
;             for (int i = 0; i < 32; ++i) {
;                 float s0 = (cl == i) ? 1.0f : 0.0f, s1 = 0.f, s2 = 0.f, s3 = 0.f;
;                 f32x4 lr[8];
; #pragma unroll
;                 for (int j4 = 0; j4 < (i + 3) / 4; ++j4) lr[j4] = *(const LAS f32x4*)(Lblk + i * 64 + j4 * 4);
;                 __builtin_amdgcn_sched_barrier(0);
; #pragma unroll
;                 for (int j4 = 0; j4 < (i + 3) / 4; ++j4) {
;                     const f32x4 l4 = lr[j4];
;                     if (j4 * 4 + 0 < i) s0 -= l4[0] * Tc[j4 * 4 + 0];
;                     if (j4 * 4 + 1 < i) s1 -= l4[1] * Tc[j4 * 4 + 1];
;                     if (j4 * 4 + 2 < i) s2 -= l4[2] * Tc[j4 * 4 + 2];
;                     if (j4 * 4 + 3 < i) s3 -= l4[3] * Tc[j4 * 4 + 3];
;                 }
;                 Tc[i] = (s0 + s1) + (s2 + s3);
;             }
.LBB0_491:
	s_andn2_b64 vcc, exec, s[0:1]
	s_cbranch_vccnz .LBB0_499
	v_ashrrev_i32_e32 v32, 1, v67
	v_and_b32_e32 v34, 1, v67
	v_lshlrev_b32_e32 v33, 8, v32
	v_lshlrev_b32_e32 v35, 6, v34
	v_readlane_b32 s1, v255, 7
	v_lshlrev_b32_e32 v32, 6, v32
	s_add_i32 s2, 0, 0x25000
	v_add3_u32 v33, s1, v33, v35
	ds_read_b128 v[44:47], v33 offset:8192
	ds_read_b128 v[48:51], v33 offset:8208
	ds_read_b128 v[52:55], v33 offset:8224
	ds_read_b128 v[56:59], v33 offset:8240
	v_lshlrev_b32_e32 v34, 5, v34
	s_waitcnt lgkmcnt(3)
	v_bfe_u32 v35, v44, 16, 1
	v_add3_u32 v35, v44, v35, s68
	v_bfe_u32 v37, v45, 16, 1
	v_lshrrev_b32_e32 v35, 16, v35
	v_add3_u32 v37, v45, v37, s68
	v_and_or_b32 v44, v37, s39, v35
	v_bfe_u32 v35, v46, 16, 1
	v_add3_u32 v35, v46, v35, s68
	v_bfe_u32 v37, v47, 16, 1
	v_lshrrev_b32_e32 v35, 16, v35
	v_add3_u32 v37, v47, v37, s68
	v_and_or_b32 v45, v37, s39, v35
	s_waitcnt lgkmcnt(2)
	v_bfe_u32 v35, v48, 16, 1
	v_add3_u32 v35, v48, v35, s68
	v_bfe_u32 v37, v49, 16, 1
	v_lshrrev_b32_e32 v35, 16, v35
	v_add3_u32 v37, v49, v37, s68
	v_and_or_b32 v46, v37, s39, v35
	v_bfe_u32 v35, v50, 16, 1
	v_add3_u32 v35, v50, v35, s68
	v_bfe_u32 v37, v51, 16, 1
	v_lshrrev_b32_e32 v35, 16, v35
	v_add3_u32 v37, v51, v37, s68
	v_and_or_b32 v47, v37, s39, v35
	s_waitcnt lgkmcnt(1)
	v_bfe_u32 v35, v52, 16, 1
	v_add3_u32 v35, v52, v35, s68
	v_bfe_u32 v37, v53, 16, 1
	v_lshrrev_b32_e32 v35, 16, v35
	v_add3_u32 v37, v53, v37, s68
	v_and_or_b32 v48, v37, s39, v35
	v_bfe_u32 v35, v54, 16, 1
	v_add3_u32 v35, v54, v35, s68
	v_bfe_u32 v37, v55, 16, 1
	v_lshrrev_b32_e32 v35, 16, v35
	v_add3_u32 v37, v55, v37, s68
	v_and_or_b32 v49, v37, s39, v35
	s_waitcnt lgkmcnt(0)
	v_bfe_u32 v35, v56, 16, 1
	v_add3_u32 v35, v56, v35, s68
	v_bfe_u32 v37, v57, 16, 1
	v_lshrrev_b32_e32 v35, 16, v35
	v_add3_u32 v37, v57, v37, s68
	v_and_or_b32 v50, v37, s39, v35
	v_bfe_u32 v35, v58, 16, 1
	v_add3_u32 v35, v58, v35, s68
	v_bfe_u32 v37, v59, 16, 1
	v_ashrrev_i32_e32 v36, 5, v67
	v_and_b32_e32 v33, 31, v67
	v_lshrrev_b32_e32 v35, 16, v35
	v_add3_u32 v37, v59, v37, s68
	v_add3_u32 v32, s2, v32, v34
	s_movk_i32 s0, 0x2080
	v_and_or_b32 v51, v37, s39, v35
	ds_write_b128 v32, v[44:47]
	ds_write_b128 v32, v[48:51] offset:16
	v_mul_lo_u32 v32, v36, s0
	v_cmp_eq_u32_e32 vcc, 0, v33
	v_add_u32_e32 v49, s1, v32
	v_mov_b32_e32 v174, v49
	ds_read_b128 v[44:47], v174 offset:256
	v_mov_b64_e32 v[124:125], 0
	v_mov_b64_e32 v[126:127], 0
	v_mov_b64_e32 v[128:129], 0
	v_mov_b64_e32 v[130:131], 0
	v_mov_b64_e32 v[150:151], 0
	v_mov_b64_e32 v[152:153], 0
	v_mov_b64_e32 v[206:207], 0
	v_mov_b64_e32 v[208:209], 0
	v_mov_b64_e32 v[210:211], 0
	v_mov_b64_e32 v[212:213], 0
	v_mov_b64_e32 v[214:215], 0
	v_mov_b64_e32 v[216:217], 0
	v_mov_b64_e32 v[218:219], 0
	v_mov_b64_e32 v[220:221], 0
	v_mov_b64_e32 v[146:147], 0
	v_mov_b64_e32 v[172:173], 0
	v_cndmask_b32_e64 v124, 0, 1.0, vcc
	v_cmp_eq_u32_e32 vcc, 1, v33
	v_mov_b32_e32 v35, 0
	v_mov_b64_e32 v[38:39], 0
	v_cndmask_b32_e64 v34, 0, 1.0, vcc
	v_cmp_eq_u32_e32 vcc, 2, v33
	s_waitcnt lgkmcnt(0)
	v_pk_fma_f32 v[34:35], v[124:125], v[44:45], v[34:35] neg_lo:[1,0,0] neg_hi:[1,0,0]
	v_pk_fma_f32 v[38:39], v[126:127], v[46:47], v[38:39] neg_lo:[1,0,0] neg_hi:[1,0,0]
	ds_read_b128 v[44:47], v174 offset:512
	v_cndmask_b32_e64 v132, 0, 1.0, vcc
	v_mov_b32_e32 v133, 0
	v_mov_b64_e32 v[144:145], 0
	v_add_f32_e32 v122, v34, v35
	v_add_f32_e32 v123, v38, v39
	v_add_f32_e32 v125, v122, v123
	v_cmp_eq_u32_e32 vcc, 3, v33
	s_waitcnt lgkmcnt(0)
	v_pk_fma_f32 v[132:133], v[124:125], v[44:45], v[132:133] neg_lo:[1,0,0] neg_hi:[1,0,0]
	v_pk_fma_f32 v[144:145], v[126:127], v[46:47], v[144:145] neg_lo:[1,0,0] neg_hi:[1,0,0]
	ds_read_b128 v[44:47], v174 offset:768
	v_cndmask_b32_e64 v34, 0, 1.0, vcc
	v_mov_b32_e32 v35, 0
	v_mov_b64_e32 v[38:39], 0
	v_add_f32_e32 v122, v132, v133
	v_add_f32_e32 v123, v144, v145
	v_add_f32_e32 v126, v122, v123
	v_cmp_eq_u32_e32 vcc, 4, v33
	s_waitcnt lgkmcnt(0)
	v_pk_fma_f32 v[34:35], v[124:125], v[44:45], v[34:35] neg_lo:[1,0,0] neg_hi:[1,0,0]
	v_pk_fma_f32 v[38:39], v[126:127], v[46:47], v[38:39] neg_lo:[1,0,0] neg_hi:[1,0,0]
	ds_read_b128 v[44:47], v174 offset:1024
	v_cndmask_b32_e64 v132, 0, 1.0, vcc
	v_mov_b32_e32 v133, 0
	v_mov_b64_e32 v[144:145], 0
	v_add_f32_e32 v122, v34, v35
	v_add_f32_e32 v123, v38, v39
	v_add_f32_e32 v127, v122, v123
	ds_read_b128 v[48:51], v174 offset:1296
	v_cmp_eq_u32_e32 vcc, 5, v33
	s_waitcnt lgkmcnt(1)
	v_pk_fma_f32 v[132:133], v[124:125], v[44:45], v[132:133] neg_lo:[1,0,0] neg_hi:[1,0,0]
	v_pk_fma_f32 v[144:145], v[126:127], v[46:47], v[144:145] neg_lo:[1,0,0] neg_hi:[1,0,0]
	ds_read_b128 v[44:47], v174 offset:1280
	v_cndmask_b32_e64 v34, 0, 1.0, vcc
	v_mov_b32_e32 v35, 0
	v_mov_b64_e32 v[38:39], 0
	v_add_f32_e32 v122, v132, v133
	v_add_f32_e32 v123, v144, v145
	v_add_f32_e32 v128, v122, v123
	v_cmp_eq_u32_e32 vcc, 6, v33
	s_waitcnt lgkmcnt(0)
	v_pk_fma_f32 v[34:35], v[124:125], v[44:45], v[34:35] neg_lo:[1,0,0] neg_hi:[1,0,0]
	v_pk_fma_f32 v[38:39], v[126:127], v[46:47], v[38:39] neg_lo:[1,0,0] neg_hi:[1,0,0]
	ds_read_b128 v[44:47], v174 offset:1536
	v_cndmask_b32_e64 v132, 0, 1.0, vcc
	v_mov_b32_e32 v133, 0
	v_mov_b64_e32 v[144:145], 0
	s_waitcnt lgkmcnt(2)
	v_pk_fma_f32 v[34:35], v[128:129], v[48:49], v[34:35] neg_lo:[1,0,0] neg_hi:[1,0,0]
	v_pk_fma_f32 v[38:39], v[130:131], v[50:51], v[38:39] neg_lo:[1,0,0] neg_hi:[1,0,0]
	ds_read_b128 v[48:51], v174 offset:1552
	v_add_f32_e32 v122, v34, v35
	v_add_f32_e32 v123, v38, v39
	v_add_f32_e32 v129, v122, v123
	v_cmp_eq_u32_e32 vcc, 7, v33
	s_waitcnt lgkmcnt(1)
; #define LAS __attribute__((address_space(3)))
; DI void gdn_unit(const Params& P, bf16_t* proj, const float* gb, int b, int h, LAS unsigned char* lds) {
;     ...
; #pragma unroll
;             for (int i = 0; i < 32; ++i) {
;                 float s0 = (cl == i) ? 1.0f : 0.0f, s1 = 0.f, s2 = 0.f, s3 = 0.f;
;                 f32x4 lr[8];
; #pragma unroll
;                 for (int j4 = 0; j4 < (i + 3) / 4; ++j4) lr[j4] = *(const LAS f32x4*)(Lblk + i * 64 + j4 * 4);
;                 __builtin_amdgcn_sched_barrier(0);
; #pragma unroll
;                 for (int j4 = 0; j4 < (i + 3) / 4; ++j4) {
;                     const f32x4 l4 = lr[j4];
;                     if (j4 * 4 + 0 < i) s0 -= l4[0] * Tc[j4 * 4 + 0];
;                     if (j4 * 4 + 1 < i) s1 -= l4[1] * Tc[j4 * 4 + 1];
;                     if (j4 * 4 + 2 < i) s2 -= l4[2] * Tc[j4 * 4 + 2];
;                     if (j4 * 4 + 3 < i) s3 -= l4[3] * Tc[j4 * 4 + 3];
;                 }
;                 Tc[i] = (s0 + s1) + (s2 + s3);
;             }
	v_pk_fma_f32 v[132:133], v[124:125], v[44:45], v[132:133] neg_lo:[1,0,0] neg_hi:[1,0,0]
	v_pk_fma_f32 v[144:145], v[126:127], v[46:47], v[144:145] neg_lo:[1,0,0] neg_hi:[1,0,0]
	ds_read_b128 v[44:47], v174 offset:1792
	v_cndmask_b32_e64 v34, 0, 1.0, vcc
	v_mov_b32_e32 v35, 0
	v_mov_b64_e32 v[38:39], 0
	s_waitcnt lgkmcnt(1)
	v_pk_fma_f32 v[132:133], v[128:129], v[48:49], v[132:133] neg_lo:[1,0,0] neg_hi:[1,0,0]
	v_pk_fma_f32 v[144:145], v[130:131], v[50:51], v[144:145] neg_lo:[1,0,0] neg_hi:[1,0,0]
	ds_read_b128 v[48:51], v174 offset:1808
	v_add_f32_e32 v122, v132, v133
	v_add_f32_e32 v123, v144, v145
	v_add_f32_e32 v130, v122, v123
	v_cmp_eq_u32_e32 vcc, 8, v33
	s_waitcnt lgkmcnt(1)
	v_pk_fma_f32 v[34:35], v[124:125], v[44:45], v[34:35] neg_lo:[1,0,0] neg_hi:[1,0,0]
	v_pk_fma_f32 v[38:39], v[126:127], v[46:47], v[38:39] neg_lo:[1,0,0] neg_hi:[1,0,0]
	ds_read_b128 v[44:47], v174 offset:2048
	v_cndmask_b32_e64 v132, 0, 1.0, vcc
	v_mov_b32_e32 v133, 0
	v_mov_b64_e32 v[144:145], 0
	s_waitcnt lgkmcnt(1)
	v_pk_fma_f32 v[34:35], v[128:129], v[48:49], v[34:35] neg_lo:[1,0,0] neg_hi:[1,0,0]
	v_pk_fma_f32 v[38:39], v[130:131], v[50:51], v[38:39] neg_lo:[1,0,0] neg_hi:[1,0,0]
	ds_read_b128 v[48:51], v174 offset:2064
	v_add_f32_e32 v122, v34, v35
	v_add_f32_e32 v123, v38, v39
	v_add_f32_e32 v131, v122, v123
	ds_read_b128 v[52:55], v174 offset:2336
	v_cmp_eq_u32_e32 vcc, 9, v33
	s_waitcnt lgkmcnt(2)
	v_pk_fma_f32 v[132:133], v[124:125], v[44:45], v[132:133] neg_lo:[1,0,0] neg_hi:[1,0,0]
	v_pk_fma_f32 v[144:145], v[126:127], v[46:47], v[144:145] neg_lo:[1,0,0] neg_hi:[1,0,0]
	ds_read_b128 v[44:47], v174 offset:2304
	v_cndmask_b32_e64 v34, 0, 1.0, vcc
	v_mov_b32_e32 v35, 0
	v_mov_b64_e32 v[38:39], 0
	s_waitcnt lgkmcnt(2)
	v_pk_fma_f32 v[132:133], v[128:129], v[48:49], v[132:133] neg_lo:[1,0,0] neg_hi:[1,0,0]
	v_pk_fma_f32 v[144:145], v[130:131], v[50:51], v[144:145] neg_lo:[1,0,0] neg_hi:[1,0,0]
	ds_read_b128 v[48:51], v174 offset:2320
	v_add_f32_e32 v122, v132, v133
	v_add_f32_e32 v123, v144, v145
	v_add_f32_e32 v150, v122, v123
	v_cmp_eq_u32_e32 vcc, 10, v33
	s_waitcnt lgkmcnt(1)
	v_pk_fma_f32 v[34:35], v[124:125], v[44:45], v[34:35] neg_lo:[1,0,0] neg_hi:[1,0,0]
	v_pk_fma_f32 v[38:39], v[126:127], v[46:47], v[38:39] neg_lo:[1,0,0] neg_hi:[1,0,0]
	ds_read_b128 v[44:47], v174 offset:2560
	v_cndmask_b32_e64 v132, 0, 1.0, vcc
	v_mov_b32_e32 v133, 0
	v_mov_b64_e32 v[144:145], 0
	s_waitcnt lgkmcnt(1)
	v_pk_fma_f32 v[34:35], v[128:129], v[48:49], v[34:35] neg_lo:[1,0,0] neg_hi:[1,0,0]
	v_pk_fma_f32 v[38:39], v[130:131], v[50:51], v[38:39] neg_lo:[1,0,0] neg_hi:[1,0,0]
	ds_read_b128 v[48:51], v174 offset:2576
	s_waitcnt lgkmcnt(4)
	v_pk_fma_f32 v[34:35], v[150:151], v[52:53], v[34:35] neg_lo:[1,0,0] neg_hi:[1,0,0]
	v_pk_fma_f32 v[38:39], v[152:153], v[54:55], v[38:39] neg_lo:[1,0,0] neg_hi:[1,0,0]
	ds_read_b128 v[52:55], v174 offset:2592
	v_add_f32_e32 v122, v34, v35
	v_add_f32_e32 v123, v38, v39
	v_add_f32_e32 v151, v122, v123
	v_cmp_eq_u32_e32 vcc, 11, v33
	s_waitcnt lgkmcnt(2)
	v_pk_fma_f32 v[132:133], v[124:125], v[44:45], v[132:133] neg_lo:[1,0,0] neg_hi:[1,0,0]
	v_pk_fma_f32 v[144:145], v[126:127], v[46:47], v[144:145] neg_lo:[1,0,0] neg_hi:[1,0,0]
	ds_read_b128 v[44:47], v174 offset:2816
	v_cndmask_b32_e64 v34, 0, 1.0, vcc
	v_mov_b32_e32 v35, 0
	v_mov_b64_e32 v[38:39], 0
	s_waitcnt lgkmcnt(2)
	v_pk_fma_f32 v[132:133], v[128:129], v[48:49], v[132:133] neg_lo:[1,0,0] neg_hi:[1,0,0]
	v_pk_fma_f32 v[144:145], v[130:131], v[50:51], v[144:145] neg_lo:[1,0,0] neg_hi:[1,0,0]
	ds_read_b128 v[48:51], v174 offset:2832
	s_waitcnt lgkmcnt(2)
	v_pk_fma_f32 v[132:133], v[150:151], v[52:53], v[132:133] neg_lo:[1,0,0] neg_hi:[1,0,0]
	v_pk_fma_f32 v[144:145], v[152:153], v[54:55], v[144:145] neg_lo:[1,0,0] neg_hi:[1,0,0]
	ds_read_b128 v[52:55], v174 offset:2848
	v_add_f32_e32 v122, v132, v133
	v_add_f32_e32 v123, v144, v145
	v_add_f32_e32 v152, v122, v123
	v_cmp_eq_u32_e32 vcc, 12, v33
	s_waitcnt lgkmcnt(2)
	v_pk_fma_f32 v[34:35], v[124:125], v[44:45], v[34:35] neg_lo:[1,0,0] neg_hi:[1,0,0]
	v_pk_fma_f32 v[38:39], v[126:127], v[46:47], v[38:39] neg_lo:[1,0,0] neg_hi:[1,0,0]
	ds_read_b128 v[44:47], v174 offset:3072
	v_cndmask_b32_e64 v132, 0, 1.0, vcc
	v_mov_b32_e32 v133, 0
	v_mov_b64_e32 v[144:145], 0
	s_waitcnt lgkmcnt(2)
	v_pk_fma_f32 v[34:35], v[128:129], v[48:49], v[34:35] neg_lo:[1,0,0] neg_hi:[1,0,0]
	v_pk_fma_f32 v[38:39], v[130:131], v[50:51], v[38:39] neg_lo:[1,0,0] neg_hi:[1,0,0]
	ds_read_b128 v[48:51], v174 offset:3088
	s_waitcnt lgkmcnt(2)
	v_pk_fma_f32 v[34:35], v[150:151], v[52:53], v[34:35] neg_lo:[1,0,0] neg_hi:[1,0,0]
	v_pk_fma_f32 v[38:39], v[152:153], v[54:55], v[38:39] neg_lo:[1,0,0] neg_hi:[1,0,0]
	ds_read_b128 v[52:55], v174 offset:3104
	v_add_f32_e32 v122, v34, v35
	v_add_f32_e32 v123, v38, v39
	v_add_f32_e32 v153, v122, v123
	ds_read_b128 v[56:59], v174 offset:3376
	v_cmp_eq_u32_e32 vcc, 13, v33
	s_waitcnt lgkmcnt(3)
	v_pk_fma_f32 v[132:133], v[124:125], v[44:45], v[132:133] neg_lo:[1,0,0] neg_hi:[1,0,0]
	v_pk_fma_f32 v[144:145], v[126:127], v[46:47], v[144:145] neg_lo:[1,0,0] neg_hi:[1,0,0]
	ds_read_b128 v[44:47], v174 offset:3328
	v_cndmask_b32_e64 v34, 0, 1.0, vcc
	v_mov_b32_e32 v35, 0
	v_mov_b64_e32 v[38:39], 0
	s_waitcnt lgkmcnt(3)
	v_pk_fma_f32 v[132:133], v[128:129], v[48:49], v[132:133] neg_lo:[1,0,0] neg_hi:[1,0,0]
	v_pk_fma_f32 v[144:145], v[130:131], v[50:51], v[144:145] neg_lo:[1,0,0] neg_hi:[1,0,0]
	ds_read_b128 v[48:51], v174 offset:3344
	s_waitcnt lgkmcnt(3)
; #define LAS __attribute__((address_space(3)))
; DI void gdn_unit(const Params& P, bf16_t* proj, const float* gb, int b, int h, LAS unsigned char* lds) {
;     ...
; #pragma unroll
;             for (int i = 0; i < 32; ++i) {
;                 float s0 = (cl == i) ? 1.0f : 0.0f, s1 = 0.f, s2 = 0.f, s3 = 0.f;
;                 f32x4 lr[8];
; #pragma unroll
;                 for (int j4 = 0; j4 < (i + 3) / 4; ++j4) lr[j4] = *(const LAS f32x4*)(Lblk + i * 64 + j4 * 4);
;                 __builtin_amdgcn_sched_barrier(0);
; #pragma unroll
;                 for (int j4 = 0; j4 < (i + 3) / 4; ++j4) {
;                     const f32x4 l4 = lr[j4];
;                     if (j4 * 4 + 0 < i) s0 -= l4[0] * Tc[j4 * 4 + 0];
;                     if (j4 * 4 + 1 < i) s1 -= l4[1] * Tc[j4 * 4 + 1];
;                     if (j4 * 4 + 2 < i) s2 -= l4[2] * Tc[j4 * 4 + 2];
;                     if (j4 * 4 + 3 < i) s3 -= l4[3] * Tc[j4 * 4 + 3];
;                 }
;                 Tc[i] = (s0 + s1) + (s2 + s3);
;             }
	v_pk_fma_f32 v[132:133], v[150:151], v[52:53], v[132:133] neg_lo:[1,0,0] neg_hi:[1,0,0]
	v_pk_fma_f32 v[144:145], v[152:153], v[54:55], v[144:145] neg_lo:[1,0,0] neg_hi:[1,0,0]
	ds_read_b128 v[52:55], v174 offset:3360
	v_add_f32_e32 v122, v132, v133
	v_add_f32_e32 v123, v144, v145
	v_add_f32_e32 v206, v122, v123
	v_cmp_eq_u32_e32 vcc, 14, v33
	s_waitcnt lgkmcnt(2)
	v_pk_fma_f32 v[34:35], v[124:125], v[44:45], v[34:35] neg_lo:[1,0,0] neg_hi:[1,0,0]
	v_pk_fma_f32 v[38:39], v[126:127], v[46:47], v[38:39] neg_lo:[1,0,0] neg_hi:[1,0,0]
	ds_read_b128 v[44:47], v174 offset:3584
	v_cndmask_b32_e64 v132, 0, 1.0, vcc
	v_mov_b32_e32 v133, 0
	v_mov_b64_e32 v[144:145], 0
	s_waitcnt lgkmcnt(2)
	v_pk_fma_f32 v[34:35], v[128:129], v[48:49], v[34:35] neg_lo:[1,0,0] neg_hi:[1,0,0]
	v_pk_fma_f32 v[38:39], v[130:131], v[50:51], v[38:39] neg_lo:[1,0,0] neg_hi:[1,0,0]
	ds_read_b128 v[48:51], v174 offset:3600
	s_waitcnt lgkmcnt(2)
	v_pk_fma_f32 v[34:35], v[150:151], v[52:53], v[34:35] neg_lo:[1,0,0] neg_hi:[1,0,0]
	v_pk_fma_f32 v[38:39], v[152:153], v[54:55], v[38:39] neg_lo:[1,0,0] neg_hi:[1,0,0]
	ds_read_b128 v[52:55], v174 offset:3616
	s_waitcnt lgkmcnt(6)
	v_pk_fma_f32 v[34:35], v[206:207], v[56:57], v[34:35] neg_lo:[1,0,0] neg_hi:[1,0,0]
	v_pk_fma_f32 v[38:39], v[208:209], v[58:59], v[38:39] neg_lo:[1,0,0] neg_hi:[1,0,0]
	ds_read_b128 v[56:59], v174 offset:3632
	v_add_f32_e32 v122, v34, v35
	v_add_f32_e32 v123, v38, v39
	v_add_f32_e32 v207, v122, v123
	v_cmp_eq_u32_e32 vcc, 15, v33
	s_waitcnt lgkmcnt(3)
	v_pk_fma_f32 v[132:133], v[124:125], v[44:45], v[132:133] neg_lo:[1,0,0] neg_hi:[1,0,0]
	v_pk_fma_f32 v[144:145], v[126:127], v[46:47], v[144:145] neg_lo:[1,0,0] neg_hi:[1,0,0]
	ds_read_b128 v[44:47], v174 offset:3840
	v_cndmask_b32_e64 v34, 0, 1.0, vcc
	v_mov_b32_e32 v35, 0
	v_mov_b64_e32 v[38:39], 0
	s_waitcnt lgkmcnt(3)
	v_pk_fma_f32 v[132:133], v[128:129], v[48:49], v[132:133] neg_lo:[1,0,0] neg_hi:[1,0,0]
	v_pk_fma_f32 v[144:145], v[130:131], v[50:51], v[144:145] neg_lo:[1,0,0] neg_hi:[1,0,0]
	ds_read_b128 v[48:51], v174 offset:3856
	s_waitcnt lgkmcnt(3)
	v_pk_fma_f32 v[132:133], v[150:151], v[52:53], v[132:133] neg_lo:[1,0,0] neg_hi:[1,0,0]
	v_pk_fma_f32 v[144:145], v[152:153], v[54:55], v[144:145] neg_lo:[1,0,0] neg_hi:[1,0,0]
	ds_read_b128 v[52:55], v174 offset:3872
	s_waitcnt lgkmcnt(3)
	v_pk_fma_f32 v[132:133], v[206:207], v[56:57], v[132:133] neg_lo:[1,0,0] neg_hi:[1,0,0]
	v_pk_fma_f32 v[144:145], v[208:209], v[58:59], v[144:145] neg_lo:[1,0,0] neg_hi:[1,0,0]
	ds_read_b128 v[56:59], v174 offset:3888
	v_add_f32_e32 v122, v132, v133
	v_add_f32_e32 v123, v144, v145
	v_add_f32_e32 v208, v122, v123
	v_cmp_eq_u32_e32 vcc, 16, v33
	s_waitcnt lgkmcnt(3)
	v_pk_fma_f32 v[34:35], v[124:125], v[44:45], v[34:35] neg_lo:[1,0,0] neg_hi:[1,0,0]
	v_pk_fma_f32 v[38:39], v[126:127], v[46:47], v[38:39] neg_lo:[1,0,0] neg_hi:[1,0,0]
	ds_read_b128 v[44:47], v174 offset:4096
	v_cndmask_b32_e64 v132, 0, 1.0, vcc
	v_mov_b32_e32 v133, 0
	v_mov_b64_e32 v[144:145], 0
	s_waitcnt lgkmcnt(3)
	v_pk_fma_f32 v[34:35], v[128:129], v[48:49], v[34:35] neg_lo:[1,0,0] neg_hi:[1,0,0]
	v_pk_fma_f32 v[38:39], v[130:131], v[50:51], v[38:39] neg_lo:[1,0,0] neg_hi:[1,0,0]
	ds_read_b128 v[48:51], v174 offset:4112
	s_waitcnt lgkmcnt(3)
	v_pk_fma_f32 v[34:35], v[150:151], v[52:53], v[34:35] neg_lo:[1,0,0] neg_hi:[1,0,0]
	v_pk_fma_f32 v[38:39], v[152:153], v[54:55], v[38:39] neg_lo:[1,0,0] neg_hi:[1,0,0]
	ds_read_b128 v[52:55], v174 offset:4128
	s_waitcnt lgkmcnt(3)
	v_pk_fma_f32 v[34:35], v[206:207], v[56:57], v[34:35] neg_lo:[1,0,0] neg_hi:[1,0,0]
	v_pk_fma_f32 v[38:39], v[208:209], v[58:59], v[38:39] neg_lo:[1,0,0] neg_hi:[1,0,0]
	ds_read_b128 v[56:59], v174 offset:4144
	v_add_f32_e32 v122, v34, v35
	v_add_f32_e32 v123, v38, v39
	v_add_f32_e32 v209, v122, v123
	ds_read_b128 v[62:65], v174 offset:4416
	v_cmp_eq_u32_e32 vcc, 17, v33
	s_waitcnt lgkmcnt(4)
	v_pk_fma_f32 v[132:133], v[124:125], v[44:45], v[132:133] neg_lo:[1,0,0] neg_hi:[1,0,0]
	v_pk_fma_f32 v[144:145], v[126:127], v[46:47], v[144:145] neg_lo:[1,0,0] neg_hi:[1,0,0]
	ds_read_b128 v[44:47], v174 offset:4352
	v_cndmask_b32_e64 v34, 0, 1.0, vcc
	v_mov_b32_e32 v35, 0
	v_mov_b64_e32 v[38:39], 0
	s_waitcnt lgkmcnt(4)
	v_pk_fma_f32 v[132:133], v[128:129], v[48:49], v[132:133] neg_lo:[1,0,0] neg_hi:[1,0,0]
	v_pk_fma_f32 v[144:145], v[130:131], v[50:51], v[144:145] neg_lo:[1,0,0] neg_hi:[1,0,0]
	ds_read_b128 v[48:51], v174 offset:4368
	s_waitcnt lgkmcnt(4)
	v_pk_fma_f32 v[132:133], v[150:151], v[52:53], v[132:133] neg_lo:[1,0,0] neg_hi:[1,0,0]
	v_pk_fma_f32 v[144:145], v[152:153], v[54:55], v[144:145] neg_lo:[1,0,0] neg_hi:[1,0,0]
	ds_read_b128 v[52:55], v174 offset:4384
	s_waitcnt lgkmcnt(4)
	v_pk_fma_f32 v[132:133], v[206:207], v[56:57], v[132:133] neg_lo:[1,0,0] neg_hi:[1,0,0]
	v_pk_fma_f32 v[144:145], v[208:209], v[58:59], v[144:145] neg_lo:[1,0,0] neg_hi:[1,0,0]
	ds_read_b128 v[56:59], v174 offset:4400
	v_add_f32_e32 v122, v132, v133
	v_add_f32_e32 v123, v144, v145
	v_add_f32_e32 v210, v122, v123
	v_cmp_eq_u32_e32 vcc, 18, v33
	s_waitcnt lgkmcnt(3)
	v_pk_fma_f32 v[34:35], v[124:125], v[44:45], v[34:35] neg_lo:[1,0,0] neg_hi:[1,0,0]
	v_pk_fma_f32 v[38:39], v[126:127], v[46:47], v[38:39] neg_lo:[1,0,0] neg_hi:[1,0,0]
	ds_read_b128 v[44:47], v174 offset:4608
	v_cndmask_b32_e64 v132, 0, 1.0, vcc
	v_mov_b32_e32 v133, 0
	v_mov_b64_e32 v[144:145], 0
	s_waitcnt lgkmcnt(3)
	v_pk_fma_f32 v[34:35], v[128:129], v[48:49], v[34:35] neg_lo:[1,0,0] neg_hi:[1,0,0]
	v_pk_fma_f32 v[38:39], v[130:131], v[50:51], v[38:39] neg_lo:[1,0,0] neg_hi:[1,0,0]
	ds_read_b128 v[48:51], v174 offset:4624
	s_waitcnt lgkmcnt(3)
; #define LAS __attribute__((address_space(3)))
; DI void gdn_unit(const Params& P, bf16_t* proj, const float* gb, int b, int h, LAS unsigned char* lds) {
;     ...
; #pragma unroll
;             for (int i = 0; i < 32; ++i) {
;                 float s0 = (cl == i) ? 1.0f : 0.0f, s1 = 0.f, s2 = 0.f, s3 = 0.f;
;                 f32x4 lr[8];
; #pragma unroll
;                 for (int j4 = 0; j4 < (i + 3) / 4; ++j4) lr[j4] = *(const LAS f32x4*)(Lblk + i * 64 + j4 * 4);
;                 __builtin_amdgcn_sched_barrier(0);
; #pragma unroll
;                 for (int j4 = 0; j4 < (i + 3) / 4; ++j4) {
;                     const f32x4 l4 = lr[j4];
;                     if (j4 * 4 + 0 < i) s0 -= l4[0] * Tc[j4 * 4 + 0];
;                     if (j4 * 4 + 1 < i) s1 -= l4[1] * Tc[j4 * 4 + 1];
;                     if (j4 * 4 + 2 < i) s2 -= l4[2] * Tc[j4 * 4 + 2];
;                     if (j4 * 4 + 3 < i) s3 -= l4[3] * Tc[j4 * 4 + 3];
;                 }
;                 Tc[i] = (s0 + s1) + (s2 + s3);
;             }
	v_pk_fma_f32 v[34:35], v[150:151], v[52:53], v[34:35] neg_lo:[1,0,0] neg_hi:[1,0,0]
	v_pk_fma_f32 v[38:39], v[152:153], v[54:55], v[38:39] neg_lo:[1,0,0] neg_hi:[1,0,0]
	ds_read_b128 v[52:55], v174 offset:4640
	s_waitcnt lgkmcnt(3)
	v_pk_fma_f32 v[34:35], v[206:207], v[56:57], v[34:35] neg_lo:[1,0,0] neg_hi:[1,0,0]
	v_pk_fma_f32 v[38:39], v[208:209], v[58:59], v[38:39] neg_lo:[1,0,0] neg_hi:[1,0,0]
	ds_read_b128 v[56:59], v174 offset:4656
	s_waitcnt lgkmcnt(8)
	v_pk_fma_f32 v[34:35], v[210:211], v[62:63], v[34:35] neg_lo:[1,0,0] neg_hi:[1,0,0]
	v_pk_fma_f32 v[38:39], v[212:213], v[64:65], v[38:39] neg_lo:[1,0,0] neg_hi:[1,0,0]
	ds_read_b128 v[62:65], v174 offset:4672
	v_add_f32_e32 v122, v34, v35
	v_add_f32_e32 v123, v38, v39
	v_add_f32_e32 v211, v122, v123
	v_cmp_eq_u32_e32 vcc, 19, v33
	s_waitcnt lgkmcnt(4)
	v_pk_fma_f32 v[132:133], v[124:125], v[44:45], v[132:133] neg_lo:[1,0,0] neg_hi:[1,0,0]
	v_pk_fma_f32 v[144:145], v[126:127], v[46:47], v[144:145] neg_lo:[1,0,0] neg_hi:[1,0,0]
	ds_read_b128 v[44:47], v174 offset:4864
	v_cndmask_b32_e64 v34, 0, 1.0, vcc
	v_mov_b32_e32 v35, 0
	v_mov_b64_e32 v[38:39], 0
	s_waitcnt lgkmcnt(4)
	v_pk_fma_f32 v[132:133], v[128:129], v[48:49], v[132:133] neg_lo:[1,0,0] neg_hi:[1,0,0]
	v_pk_fma_f32 v[144:145], v[130:131], v[50:51], v[144:145] neg_lo:[1,0,0] neg_hi:[1,0,0]
	ds_read_b128 v[48:51], v174 offset:4880
	s_waitcnt lgkmcnt(4)
	v_pk_fma_f32 v[132:133], v[150:151], v[52:53], v[132:133] neg_lo:[1,0,0] neg_hi:[1,0,0]
	v_pk_fma_f32 v[144:145], v[152:153], v[54:55], v[144:145] neg_lo:[1,0,0] neg_hi:[1,0,0]
	ds_read_b128 v[52:55], v174 offset:4896
	s_waitcnt lgkmcnt(4)
	v_pk_fma_f32 v[132:133], v[206:207], v[56:57], v[132:133] neg_lo:[1,0,0] neg_hi:[1,0,0]
	v_pk_fma_f32 v[144:145], v[208:209], v[58:59], v[144:145] neg_lo:[1,0,0] neg_hi:[1,0,0]
	ds_read_b128 v[56:59], v174 offset:4912
	s_waitcnt lgkmcnt(4)
	v_pk_fma_f32 v[132:133], v[210:211], v[62:63], v[132:133] neg_lo:[1,0,0] neg_hi:[1,0,0]
	v_pk_fma_f32 v[144:145], v[212:213], v[64:65], v[144:145] neg_lo:[1,0,0] neg_hi:[1,0,0]
	ds_read_b128 v[62:65], v174 offset:4928
	v_add_f32_e32 v122, v132, v133
	v_add_f32_e32 v123, v144, v145
	v_add_f32_e32 v212, v122, v123
	v_cmp_eq_u32_e32 vcc, 20, v33
	s_waitcnt lgkmcnt(4)
	v_pk_fma_f32 v[34:35], v[124:125], v[44:45], v[34:35] neg_lo:[1,0,0] neg_hi:[1,0,0]
	v_pk_fma_f32 v[38:39], v[126:127], v[46:47], v[38:39] neg_lo:[1,0,0] neg_hi:[1,0,0]
	ds_read_b128 v[44:47], v174 offset:5120
	v_cndmask_b32_e64 v132, 0, 1.0, vcc
	v_mov_b32_e32 v133, 0
	v_mov_b64_e32 v[144:145], 0
	s_waitcnt lgkmcnt(4)
	v_pk_fma_f32 v[34:35], v[128:129], v[48:49], v[34:35] neg_lo:[1,0,0] neg_hi:[1,0,0]
	v_pk_fma_f32 v[38:39], v[130:131], v[50:51], v[38:39] neg_lo:[1,0,0] neg_hi:[1,0,0]
	ds_read_b128 v[48:51], v174 offset:5136
	s_waitcnt lgkmcnt(4)
	v_pk_fma_f32 v[34:35], v[150:151], v[52:53], v[34:35] neg_lo:[1,0,0] neg_hi:[1,0,0]
	v_pk_fma_f32 v[38:39], v[152:153], v[54:55], v[38:39] neg_lo:[1,0,0] neg_hi:[1,0,0]
	ds_read_b128 v[52:55], v174 offset:5152
	s_waitcnt lgkmcnt(4)
	v_pk_fma_f32 v[34:35], v[206:207], v[56:57], v[34:35] neg_lo:[1,0,0] neg_hi:[1,0,0]
	v_pk_fma_f32 v[38:39], v[208:209], v[58:59], v[38:39] neg_lo:[1,0,0] neg_hi:[1,0,0]
	ds_read_b128 v[56:59], v174 offset:5168
	s_waitcnt lgkmcnt(4)
	v_pk_fma_f32 v[34:35], v[210:211], v[62:63], v[34:35] neg_lo:[1,0,0] neg_hi:[1,0,0]
	v_pk_fma_f32 v[38:39], v[212:213], v[64:65], v[38:39] neg_lo:[1,0,0] neg_hi:[1,0,0]
	ds_read_b128 v[62:65], v174 offset:5184
	v_add_f32_e32 v122, v34, v35
	v_add_f32_e32 v123, v38, v39
	v_add_f32_e32 v213, v122, v123
	ds_read_b128 v[114:117], v174 offset:5456
	v_cmp_eq_u32_e32 vcc, 21, v33
	s_waitcnt lgkmcnt(5)
	v_pk_fma_f32 v[132:133], v[124:125], v[44:45], v[132:133] neg_lo:[1,0,0] neg_hi:[1,0,0]
	v_pk_fma_f32 v[144:145], v[126:127], v[46:47], v[144:145] neg_lo:[1,0,0] neg_hi:[1,0,0]
	ds_read_b128 v[44:47], v174 offset:5376
	v_cndmask_b32_e64 v34, 0, 1.0, vcc
	v_mov_b32_e32 v35, 0
	v_mov_b64_e32 v[38:39], 0
	s_waitcnt lgkmcnt(5)
	v_pk_fma_f32 v[132:133], v[128:129], v[48:49], v[132:133] neg_lo:[1,0,0] neg_hi:[1,0,0]
	v_pk_fma_f32 v[144:145], v[130:131], v[50:51], v[144:145] neg_lo:[1,0,0] neg_hi:[1,0,0]
	ds_read_b128 v[48:51], v174 offset:5392
	s_waitcnt lgkmcnt(5)
	v_pk_fma_f32 v[132:133], v[150:151], v[52:53], v[132:133] neg_lo:[1,0,0] neg_hi:[1,0,0]
	v_pk_fma_f32 v[144:145], v[152:153], v[54:55], v[144:145] neg_lo:[1,0,0] neg_hi:[1,0,0]
	ds_read_b128 v[52:55], v174 offset:5408
	s_waitcnt lgkmcnt(5)
	v_pk_fma_f32 v[132:133], v[206:207], v[56:57], v[132:133] neg_lo:[1,0,0] neg_hi:[1,0,0]
	v_pk_fma_f32 v[144:145], v[208:209], v[58:59], v[144:145] neg_lo:[1,0,0] neg_hi:[1,0,0]
	ds_read_b128 v[56:59], v174 offset:5424
	s_waitcnt lgkmcnt(5)
	v_pk_fma_f32 v[132:133], v[210:211], v[62:63], v[132:133] neg_lo:[1,0,0] neg_hi:[1,0,0]
	v_pk_fma_f32 v[144:145], v[212:213], v[64:65], v[144:145] neg_lo:[1,0,0] neg_hi:[1,0,0]
	ds_read_b128 v[62:65], v174 offset:5440
	v_add_f32_e32 v122, v132, v133
	v_add_f32_e32 v123, v144, v145
	v_add_f32_e32 v214, v122, v123
	v_cmp_eq_u32_e32 vcc, 22, v33
	s_waitcnt lgkmcnt(4)
	v_pk_fma_f32 v[34:35], v[124:125], v[44:45], v[34:35] neg_lo:[1,0,0] neg_hi:[1,0,0]
	v_pk_fma_f32 v[38:39], v[126:127], v[46:47], v[38:39] neg_lo:[1,0,0] neg_hi:[1,0,0]
	ds_read_b128 v[44:47], v174 offset:5632
	v_cndmask_b32_e64 v132, 0, 1.0, vcc
	v_mov_b32_e32 v133, 0
	v_mov_b64_e32 v[144:145], 0
	s_waitcnt lgkmcnt(4)
	v_pk_fma_f32 v[34:35], v[128:129], v[48:49], v[34:35] neg_lo:[1,0,0] neg_hi:[1,0,0]
	v_pk_fma_f32 v[38:39], v[130:131], v[50:51], v[38:39] neg_lo:[1,0,0] neg_hi:[1,0,0]
	ds_read_b128 v[48:51], v174 offset:5648
	s_waitcnt lgkmcnt(4)
; #define LAS __attribute__((address_space(3)))
; DI void gdn_unit(const Params& P, bf16_t* proj, const float* gb, int b, int h, LAS unsigned char* lds) {
;     ...
; #pragma unroll
;             for (int i = 0; i < 32; ++i) {
;                 float s0 = (cl == i) ? 1.0f : 0.0f, s1 = 0.f, s2 = 0.f, s3 = 0.f;
;                 f32x4 lr[8];
; #pragma unroll
;                 for (int j4 = 0; j4 < (i + 3) / 4; ++j4) lr[j4] = *(const LAS f32x4*)(Lblk + i * 64 + j4 * 4);
;                 __builtin_amdgcn_sched_barrier(0);
; #pragma unroll
;                 for (int j4 = 0; j4 < (i + 3) / 4; ++j4) {
;                     const f32x4 l4 = lr[j4];
;                     if (j4 * 4 + 0 < i) s0 -= l4[0] * Tc[j4 * 4 + 0];
;                     if (j4 * 4 + 1 < i) s1 -= l4[1] * Tc[j4 * 4 + 1];
;                     if (j4 * 4 + 2 < i) s2 -= l4[2] * Tc[j4 * 4 + 2];
;                     if (j4 * 4 + 3 < i) s3 -= l4[3] * Tc[j4 * 4 + 3];
;                 }
;                 Tc[i] = (s0 + s1) + (s2 + s3);
;             }
	v_pk_fma_f32 v[34:35], v[150:151], v[52:53], v[34:35] neg_lo:[1,0,0] neg_hi:[1,0,0]
	v_pk_fma_f32 v[38:39], v[152:153], v[54:55], v[38:39] neg_lo:[1,0,0] neg_hi:[1,0,0]
	ds_read_b128 v[52:55], v174 offset:5664
	s_waitcnt lgkmcnt(4)
	v_pk_fma_f32 v[34:35], v[206:207], v[56:57], v[34:35] neg_lo:[1,0,0] neg_hi:[1,0,0]
	v_pk_fma_f32 v[38:39], v[208:209], v[58:59], v[38:39] neg_lo:[1,0,0] neg_hi:[1,0,0]
	ds_read_b128 v[56:59], v174 offset:5680
	s_waitcnt lgkmcnt(4)
	v_pk_fma_f32 v[34:35], v[210:211], v[62:63], v[34:35] neg_lo:[1,0,0] neg_hi:[1,0,0]
	v_pk_fma_f32 v[38:39], v[212:213], v[64:65], v[38:39] neg_lo:[1,0,0] neg_hi:[1,0,0]
	ds_read_b128 v[62:65], v174 offset:5696
	s_waitcnt lgkmcnt(10)
	v_pk_fma_f32 v[34:35], v[214:215], v[114:115], v[34:35] neg_lo:[1,0,0] neg_hi:[1,0,0]
	v_pk_fma_f32 v[38:39], v[216:217], v[116:117], v[38:39] neg_lo:[1,0,0] neg_hi:[1,0,0]
	ds_read_b128 v[114:117], v174 offset:5712
	v_add_f32_e32 v122, v34, v35
	v_add_f32_e32 v123, v38, v39
	v_add_f32_e32 v215, v122, v123
	v_cmp_eq_u32_e32 vcc, 23, v33
	s_waitcnt lgkmcnt(5)
	v_pk_fma_f32 v[132:133], v[124:125], v[44:45], v[132:133] neg_lo:[1,0,0] neg_hi:[1,0,0]
	v_pk_fma_f32 v[144:145], v[126:127], v[46:47], v[144:145] neg_lo:[1,0,0] neg_hi:[1,0,0]
	ds_read_b128 v[44:47], v174 offset:5888
	v_cndmask_b32_e64 v34, 0, 1.0, vcc
	v_mov_b32_e32 v35, 0
	v_mov_b64_e32 v[38:39], 0
	s_waitcnt lgkmcnt(5)
	v_pk_fma_f32 v[132:133], v[128:129], v[48:49], v[132:133] neg_lo:[1,0,0] neg_hi:[1,0,0]
	v_pk_fma_f32 v[144:145], v[130:131], v[50:51], v[144:145] neg_lo:[1,0,0] neg_hi:[1,0,0]
	ds_read_b128 v[48:51], v174 offset:5904
	s_waitcnt lgkmcnt(5)
	v_pk_fma_f32 v[132:133], v[150:151], v[52:53], v[132:133] neg_lo:[1,0,0] neg_hi:[1,0,0]
	v_pk_fma_f32 v[144:145], v[152:153], v[54:55], v[144:145] neg_lo:[1,0,0] neg_hi:[1,0,0]
	ds_read_b128 v[52:55], v174 offset:5920
	s_waitcnt lgkmcnt(5)
	v_pk_fma_f32 v[132:133], v[206:207], v[56:57], v[132:133] neg_lo:[1,0,0] neg_hi:[1,0,0]
	v_pk_fma_f32 v[144:145], v[208:209], v[58:59], v[144:145] neg_lo:[1,0,0] neg_hi:[1,0,0]
	ds_read_b128 v[56:59], v174 offset:5936
	s_waitcnt lgkmcnt(5)
	v_pk_fma_f32 v[132:133], v[210:211], v[62:63], v[132:133] neg_lo:[1,0,0] neg_hi:[1,0,0]
	v_pk_fma_f32 v[144:145], v[212:213], v[64:65], v[144:145] neg_lo:[1,0,0] neg_hi:[1,0,0]
	ds_read_b128 v[62:65], v174 offset:5952
	s_waitcnt lgkmcnt(5)
	v_pk_fma_f32 v[132:133], v[214:215], v[114:115], v[132:133] neg_lo:[1,0,0] neg_hi:[1,0,0]
	v_pk_fma_f32 v[144:145], v[216:217], v[116:117], v[144:145] neg_lo:[1,0,0] neg_hi:[1,0,0]
	ds_read_b128 v[114:117], v174 offset:5968
	v_add_f32_e32 v122, v132, v133
	v_add_f32_e32 v123, v144, v145
	v_add_f32_e32 v216, v122, v123
	v_cmp_eq_u32_e32 vcc, 24, v33
	s_waitcnt lgkmcnt(5)
	v_pk_fma_f32 v[34:35], v[124:125], v[44:45], v[34:35] neg_lo:[1,0,0] neg_hi:[1,0,0]
	v_pk_fma_f32 v[38:39], v[126:127], v[46:47], v[38:39] neg_lo:[1,0,0] neg_hi:[1,0,0]
	ds_read_b128 v[44:47], v174 offset:6144
	v_cndmask_b32_e64 v132, 0, 1.0, vcc
	v_mov_b32_e32 v133, 0
	v_mov_b64_e32 v[144:145], 0
	s_waitcnt lgkmcnt(5)
	v_pk_fma_f32 v[34:35], v[128:129], v[48:49], v[34:35] neg_lo:[1,0,0] neg_hi:[1,0,0]
	v_pk_fma_f32 v[38:39], v[130:131], v[50:51], v[38:39] neg_lo:[1,0,0] neg_hi:[1,0,0]
	ds_read_b128 v[48:51], v174 offset:6160
	s_waitcnt lgkmcnt(5)
	v_pk_fma_f32 v[34:35], v[150:151], v[52:53], v[34:35] neg_lo:[1,0,0] neg_hi:[1,0,0]
	v_pk_fma_f32 v[38:39], v[152:153], v[54:55], v[38:39] neg_lo:[1,0,0] neg_hi:[1,0,0]
	ds_read_b128 v[52:55], v174 offset:6176
	s_waitcnt lgkmcnt(5)
	v_pk_fma_f32 v[34:35], v[206:207], v[56:57], v[34:35] neg_lo:[1,0,0] neg_hi:[1,0,0]
	v_pk_fma_f32 v[38:39], v[208:209], v[58:59], v[38:39] neg_lo:[1,0,0] neg_hi:[1,0,0]
	ds_read_b128 v[56:59], v174 offset:6192
	s_waitcnt lgkmcnt(5)
	v_pk_fma_f32 v[34:35], v[210:211], v[62:63], v[34:35] neg_lo:[1,0,0] neg_hi:[1,0,0]
	v_pk_fma_f32 v[38:39], v[212:213], v[64:65], v[38:39] neg_lo:[1,0,0] neg_hi:[1,0,0]
	ds_read_b128 v[62:65], v174 offset:6208
	s_waitcnt lgkmcnt(5)
	v_pk_fma_f32 v[34:35], v[214:215], v[114:115], v[34:35] neg_lo:[1,0,0] neg_hi:[1,0,0]
	v_pk_fma_f32 v[38:39], v[216:217], v[116:117], v[38:39] neg_lo:[1,0,0] neg_hi:[1,0,0]
	ds_read_b128 v[114:117], v174 offset:6224
	v_add_f32_e32 v122, v34, v35
	v_add_f32_e32 v123, v38, v39
	v_add_f32_e32 v217, v122, v123
	ds_read_b128 v[118:121], v174 offset:6496
	v_cmp_eq_u32_e32 vcc, 25, v33
	s_waitcnt lgkmcnt(6)
	v_pk_fma_f32 v[132:133], v[124:125], v[44:45], v[132:133] neg_lo:[1,0,0] neg_hi:[1,0,0]
	v_pk_fma_f32 v[144:145], v[126:127], v[46:47], v[144:145] neg_lo:[1,0,0] neg_hi:[1,0,0]
	ds_read_b128 v[44:47], v174 offset:6400
	v_cndmask_b32_e64 v34, 0, 1.0, vcc
	v_mov_b32_e32 v35, 0
	v_mov_b64_e32 v[38:39], 0
	s_waitcnt lgkmcnt(6)
	v_pk_fma_f32 v[132:133], v[128:129], v[48:49], v[132:133] neg_lo:[1,0,0] neg_hi:[1,0,0]
	v_pk_fma_f32 v[144:145], v[130:131], v[50:51], v[144:145] neg_lo:[1,0,0] neg_hi:[1,0,0]
	ds_read_b128 v[48:51], v174 offset:6416
	s_waitcnt lgkmcnt(6)
	v_pk_fma_f32 v[132:133], v[150:151], v[52:53], v[132:133] neg_lo:[1,0,0] neg_hi:[1,0,0]
	v_pk_fma_f32 v[144:145], v[152:153], v[54:55], v[144:145] neg_lo:[1,0,0] neg_hi:[1,0,0]
	ds_read_b128 v[52:55], v174 offset:6432
	s_waitcnt lgkmcnt(6)
	v_pk_fma_f32 v[132:133], v[206:207], v[56:57], v[132:133] neg_lo:[1,0,0] neg_hi:[1,0,0]
	v_pk_fma_f32 v[144:145], v[208:209], v[58:59], v[144:145] neg_lo:[1,0,0] neg_hi:[1,0,0]
	ds_read_b128 v[56:59], v174 offset:6448
	s_waitcnt lgkmcnt(6)
	v_pk_fma_f32 v[132:133], v[210:211], v[62:63], v[132:133] neg_lo:[1,0,0] neg_hi:[1,0,0]
	v_pk_fma_f32 v[144:145], v[212:213], v[64:65], v[144:145] neg_lo:[1,0,0] neg_hi:[1,0,0]
	ds_read_b128 v[62:65], v174 offset:6464
	s_waitcnt lgkmcnt(6)
; #define LAS __attribute__((address_space(3)))
; DI void gdn_unit(const Params& P, bf16_t* proj, const float* gb, int b, int h, LAS unsigned char* lds) {
;     ...
; #pragma unroll
;             for (int i = 0; i < 32; ++i) {
;                 float s0 = (cl == i) ? 1.0f : 0.0f, s1 = 0.f, s2 = 0.f, s3 = 0.f;
;                 f32x4 lr[8];
; #pragma unroll
;                 for (int j4 = 0; j4 < (i + 3) / 4; ++j4) lr[j4] = *(const LAS f32x4*)(Lblk + i * 64 + j4 * 4);
;                 __builtin_amdgcn_sched_barrier(0);
; #pragma unroll
;                 for (int j4 = 0; j4 < (i + 3) / 4; ++j4) {
;                     const f32x4 l4 = lr[j4];
;                     if (j4 * 4 + 0 < i) s0 -= l4[0] * Tc[j4 * 4 + 0];
;                     if (j4 * 4 + 1 < i) s1 -= l4[1] * Tc[j4 * 4 + 1];
;                     if (j4 * 4 + 2 < i) s2 -= l4[2] * Tc[j4 * 4 + 2];
;                     if (j4 * 4 + 3 < i) s3 -= l4[3] * Tc[j4 * 4 + 3];
;                 }
;                 Tc[i] = (s0 + s1) + (s2 + s3);
;             }
	v_pk_fma_f32 v[132:133], v[214:215], v[114:115], v[132:133] neg_lo:[1,0,0] neg_hi:[1,0,0]
	v_pk_fma_f32 v[144:145], v[216:217], v[116:117], v[144:145] neg_lo:[1,0,0] neg_hi:[1,0,0]
	ds_read_b128 v[114:117], v174 offset:6480
	v_add_f32_e32 v122, v132, v133
	v_add_f32_e32 v123, v144, v145
	v_add_f32_e32 v218, v122, v123
	v_cmp_eq_u32_e32 vcc, 26, v33
	s_waitcnt lgkmcnt(5)
	v_pk_fma_f32 v[34:35], v[124:125], v[44:45], v[34:35] neg_lo:[1,0,0] neg_hi:[1,0,0]
	v_pk_fma_f32 v[38:39], v[126:127], v[46:47], v[38:39] neg_lo:[1,0,0] neg_hi:[1,0,0]
	ds_read_b128 v[44:47], v174 offset:6656
	v_cndmask_b32_e64 v132, 0, 1.0, vcc
	v_mov_b32_e32 v133, 0
	v_mov_b64_e32 v[144:145], 0
	s_waitcnt lgkmcnt(5)
	v_pk_fma_f32 v[34:35], v[128:129], v[48:49], v[34:35] neg_lo:[1,0,0] neg_hi:[1,0,0]
	v_pk_fma_f32 v[38:39], v[130:131], v[50:51], v[38:39] neg_lo:[1,0,0] neg_hi:[1,0,0]
	ds_read_b128 v[48:51], v174 offset:6672
	s_waitcnt lgkmcnt(5)
	v_pk_fma_f32 v[34:35], v[150:151], v[52:53], v[34:35] neg_lo:[1,0,0] neg_hi:[1,0,0]
	v_pk_fma_f32 v[38:39], v[152:153], v[54:55], v[38:39] neg_lo:[1,0,0] neg_hi:[1,0,0]
	ds_read_b128 v[52:55], v174 offset:6688
	s_waitcnt lgkmcnt(5)
	v_pk_fma_f32 v[34:35], v[206:207], v[56:57], v[34:35] neg_lo:[1,0,0] neg_hi:[1,0,0]
	v_pk_fma_f32 v[38:39], v[208:209], v[58:59], v[38:39] neg_lo:[1,0,0] neg_hi:[1,0,0]
	ds_read_b128 v[56:59], v174 offset:6704
	s_waitcnt lgkmcnt(5)
	v_pk_fma_f32 v[34:35], v[210:211], v[62:63], v[34:35] neg_lo:[1,0,0] neg_hi:[1,0,0]
	v_pk_fma_f32 v[38:39], v[212:213], v[64:65], v[38:39] neg_lo:[1,0,0] neg_hi:[1,0,0]
	ds_read_b128 v[62:65], v174 offset:6720
	s_waitcnt lgkmcnt(5)
	v_pk_fma_f32 v[34:35], v[214:215], v[114:115], v[34:35] neg_lo:[1,0,0] neg_hi:[1,0,0]
	v_pk_fma_f32 v[38:39], v[216:217], v[116:117], v[38:39] neg_lo:[1,0,0] neg_hi:[1,0,0]
	ds_read_b128 v[114:117], v174 offset:6736
	s_waitcnt lgkmcnt(12)
	v_pk_fma_f32 v[34:35], v[218:219], v[118:119], v[34:35] neg_lo:[1,0,0] neg_hi:[1,0,0]
	v_pk_fma_f32 v[38:39], v[220:221], v[120:121], v[38:39] neg_lo:[1,0,0] neg_hi:[1,0,0]
	ds_read_b128 v[118:121], v174 offset:6752
	v_add_f32_e32 v122, v34, v35
	v_add_f32_e32 v123, v38, v39
	v_add_f32_e32 v219, v122, v123
	v_cmp_eq_u32_e32 vcc, 27, v33
	s_waitcnt lgkmcnt(6)
	v_pk_fma_f32 v[132:133], v[124:125], v[44:45], v[132:133] neg_lo:[1,0,0] neg_hi:[1,0,0]
	v_pk_fma_f32 v[144:145], v[126:127], v[46:47], v[144:145] neg_lo:[1,0,0] neg_hi:[1,0,0]
	ds_read_b128 v[44:47], v174 offset:6912
	v_cndmask_b32_e64 v34, 0, 1.0, vcc
	v_mov_b32_e32 v35, 0
	v_mov_b64_e32 v[38:39], 0
	s_waitcnt lgkmcnt(6)
	v_pk_fma_f32 v[132:133], v[128:129], v[48:49], v[132:133] neg_lo:[1,0,0] neg_hi:[1,0,0]
	v_pk_fma_f32 v[144:145], v[130:131], v[50:51], v[144:145] neg_lo:[1,0,0] neg_hi:[1,0,0]
	ds_read_b128 v[48:51], v174 offset:6928
	s_waitcnt lgkmcnt(6)
	v_pk_fma_f32 v[132:133], v[150:151], v[52:53], v[132:133] neg_lo:[1,0,0] neg_hi:[1,0,0]
	v_pk_fma_f32 v[144:145], v[152:153], v[54:55], v[144:145] neg_lo:[1,0,0] neg_hi:[1,0,0]
	ds_read_b128 v[52:55], v174 offset:6944
	s_waitcnt lgkmcnt(6)
	v_pk_fma_f32 v[132:133], v[206:207], v[56:57], v[132:133] neg_lo:[1,0,0] neg_hi:[1,0,0]
	v_pk_fma_f32 v[144:145], v[208:209], v[58:59], v[144:145] neg_lo:[1,0,0] neg_hi:[1,0,0]
	ds_read_b128 v[56:59], v174 offset:6960
	s_waitcnt lgkmcnt(6)
	v_pk_fma_f32 v[132:133], v[210:211], v[62:63], v[132:133] neg_lo:[1,0,0] neg_hi:[1,0,0]
	v_pk_fma_f32 v[144:145], v[212:213], v[64:65], v[144:145] neg_lo:[1,0,0] neg_hi:[1,0,0]
	ds_read_b128 v[62:65], v174 offset:6976
	s_waitcnt lgkmcnt(6)
	v_pk_fma_f32 v[132:133], v[214:215], v[114:115], v[132:133] neg_lo:[1,0,0] neg_hi:[1,0,0]
	v_pk_fma_f32 v[144:145], v[216:217], v[116:117], v[144:145] neg_lo:[1,0,0] neg_hi:[1,0,0]
	ds_read_b128 v[114:117], v174 offset:6992
	s_waitcnt lgkmcnt(6)
	v_pk_fma_f32 v[132:133], v[218:219], v[118:119], v[132:133] neg_lo:[1,0,0] neg_hi:[1,0,0]
	v_pk_fma_f32 v[144:145], v[220:221], v[120:121], v[144:145] neg_lo:[1,0,0] neg_hi:[1,0,0]
	ds_read_b128 v[118:121], v174 offset:7008
	v_add_f32_e32 v122, v132, v133
	v_add_f32_e32 v123, v144, v145
	v_add_f32_e32 v220, v122, v123
	v_cmp_eq_u32_e32 vcc, 28, v33
	s_waitcnt lgkmcnt(6)
	v_pk_fma_f32 v[34:35], v[124:125], v[44:45], v[34:35] neg_lo:[1,0,0] neg_hi:[1,0,0]
	v_pk_fma_f32 v[38:39], v[126:127], v[46:47], v[38:39] neg_lo:[1,0,0] neg_hi:[1,0,0]
	ds_read_b128 v[44:47], v174 offset:7168
	v_cndmask_b32_e64 v132, 0, 1.0, vcc
	v_mov_b32_e32 v133, 0
	v_mov_b64_e32 v[144:145], 0
	s_waitcnt lgkmcnt(6)
	v_pk_fma_f32 v[34:35], v[128:129], v[48:49], v[34:35] neg_lo:[1,0,0] neg_hi:[1,0,0]
	v_pk_fma_f32 v[38:39], v[130:131], v[50:51], v[38:39] neg_lo:[1,0,0] neg_hi:[1,0,0]
	ds_read_b128 v[48:51], v174 offset:7184
	s_waitcnt lgkmcnt(6)
	v_pk_fma_f32 v[34:35], v[150:151], v[52:53], v[34:35] neg_lo:[1,0,0] neg_hi:[1,0,0]
	v_pk_fma_f32 v[38:39], v[152:153], v[54:55], v[38:39] neg_lo:[1,0,0] neg_hi:[1,0,0]
	ds_read_b128 v[52:55], v174 offset:7200
	s_waitcnt lgkmcnt(6)
	v_pk_fma_f32 v[34:35], v[206:207], v[56:57], v[34:35] neg_lo:[1,0,0] neg_hi:[1,0,0]
	v_pk_fma_f32 v[38:39], v[208:209], v[58:59], v[38:39] neg_lo:[1,0,0] neg_hi:[1,0,0]
	ds_read_b128 v[56:59], v174 offset:7216
	s_waitcnt lgkmcnt(6)
	v_pk_fma_f32 v[34:35], v[210:211], v[62:63], v[34:35] neg_lo:[1,0,0] neg_hi:[1,0,0]
	v_pk_fma_f32 v[38:39], v[212:213], v[64:65], v[38:39] neg_lo:[1,0,0] neg_hi:[1,0,0]
	ds_read_b128 v[62:65], v174 offset:7232
	s_waitcnt lgkmcnt(6)
	v_pk_fma_f32 v[34:35], v[214:215], v[114:115], v[34:35] neg_lo:[1,0,0] neg_hi:[1,0,0]
	v_pk_fma_f32 v[38:39], v[216:217], v[116:117], v[38:39] neg_lo:[1,0,0] neg_hi:[1,0,0]
	ds_read_b128 v[114:117], v174 offset:7248
	s_waitcnt lgkmcnt(6)
; #define LAS __attribute__((address_space(3)))
; DI void gdn_unit(const Params& P, bf16_t* proj, const float* gb, int b, int h, LAS unsigned char* lds) {
;     ...
; #pragma unroll
;             for (int i = 0; i < 32; ++i) {
;                 float s0 = (cl == i) ? 1.0f : 0.0f, s1 = 0.f, s2 = 0.f, s3 = 0.f;
;                 f32x4 lr[8];
; #pragma unroll
;                 for (int j4 = 0; j4 < (i + 3) / 4; ++j4) lr[j4] = *(const LAS f32x4*)(Lblk + i * 64 + j4 * 4);
;                 __builtin_amdgcn_sched_barrier(0);
; #pragma unroll
;                 for (int j4 = 0; j4 < (i + 3) / 4; ++j4) {
;                     const f32x4 l4 = lr[j4];
;                     if (j4 * 4 + 0 < i) s0 -= l4[0] * Tc[j4 * 4 + 0];
;                     if (j4 * 4 + 1 < i) s1 -= l4[1] * Tc[j4 * 4 + 1];
;                     if (j4 * 4 + 2 < i) s2 -= l4[2] * Tc[j4 * 4 + 2];
;                     if (j4 * 4 + 3 < i) s3 -= l4[3] * Tc[j4 * 4 + 3];
;                 }
;                 Tc[i] = (s0 + s1) + (s2 + s3);
;             }
	v_pk_fma_f32 v[34:35], v[218:219], v[118:119], v[34:35] neg_lo:[1,0,0] neg_hi:[1,0,0]
	v_pk_fma_f32 v[38:39], v[220:221], v[120:121], v[38:39] neg_lo:[1,0,0] neg_hi:[1,0,0]
	ds_read_b128 v[118:121], v174 offset:7264
	v_add_f32_e32 v122, v34, v35
	v_add_f32_e32 v123, v38, v39
	v_add_f32_e32 v221, v122, v123
	ds_read_b128 v[138:141], v174 offset:7536
	v_cmp_eq_u32_e32 vcc, 29, v33
	s_waitcnt lgkmcnt(7)
	v_pk_fma_f32 v[132:133], v[124:125], v[44:45], v[132:133] neg_lo:[1,0,0] neg_hi:[1,0,0]
	v_pk_fma_f32 v[144:145], v[126:127], v[46:47], v[144:145] neg_lo:[1,0,0] neg_hi:[1,0,0]
	ds_read_b128 v[44:47], v174 offset:7424
	v_cndmask_b32_e64 v34, 0, 1.0, vcc
	v_mov_b32_e32 v35, 0
	v_mov_b64_e32 v[38:39], 0
	s_waitcnt lgkmcnt(7)
	v_pk_fma_f32 v[132:133], v[128:129], v[48:49], v[132:133] neg_lo:[1,0,0] neg_hi:[1,0,0]
	v_pk_fma_f32 v[144:145], v[130:131], v[50:51], v[144:145] neg_lo:[1,0,0] neg_hi:[1,0,0]
	ds_read_b128 v[48:51], v174 offset:7440
	s_waitcnt lgkmcnt(7)
	v_pk_fma_f32 v[132:133], v[150:151], v[52:53], v[132:133] neg_lo:[1,0,0] neg_hi:[1,0,0]
	v_pk_fma_f32 v[144:145], v[152:153], v[54:55], v[144:145] neg_lo:[1,0,0] neg_hi:[1,0,0]
	ds_read_b128 v[52:55], v174 offset:7456
	s_waitcnt lgkmcnt(7)
	v_pk_fma_f32 v[132:133], v[206:207], v[56:57], v[132:133] neg_lo:[1,0,0] neg_hi:[1,0,0]
	v_pk_fma_f32 v[144:145], v[208:209], v[58:59], v[144:145] neg_lo:[1,0,0] neg_hi:[1,0,0]
	ds_read_b128 v[56:59], v174 offset:7472
	s_waitcnt lgkmcnt(7)
	v_pk_fma_f32 v[132:133], v[210:211], v[62:63], v[132:133] neg_lo:[1,0,0] neg_hi:[1,0,0]
	v_pk_fma_f32 v[144:145], v[212:213], v[64:65], v[144:145] neg_lo:[1,0,0] neg_hi:[1,0,0]
	ds_read_b128 v[62:65], v174 offset:7488
	s_waitcnt lgkmcnt(7)
	v_pk_fma_f32 v[132:133], v[214:215], v[114:115], v[132:133] neg_lo:[1,0,0] neg_hi:[1,0,0]
	v_pk_fma_f32 v[144:145], v[216:217], v[116:117], v[144:145] neg_lo:[1,0,0] neg_hi:[1,0,0]
	ds_read_b128 v[114:117], v174 offset:7504
	s_waitcnt lgkmcnt(7)
	v_pk_fma_f32 v[132:133], v[218:219], v[118:119], v[132:133] neg_lo:[1,0,0] neg_hi:[1,0,0]
	v_pk_fma_f32 v[144:145], v[220:221], v[120:121], v[144:145] neg_lo:[1,0,0] neg_hi:[1,0,0]
	ds_read_b128 v[118:121], v174 offset:7520
	v_add_f32_e32 v122, v132, v133
	v_add_f32_e32 v123, v144, v145
	v_add_f32_e32 v146, v122, v123
	v_cmp_eq_u32_e32 vcc, 30, v33
	s_waitcnt lgkmcnt(6)
	v_pk_fma_f32 v[34:35], v[124:125], v[44:45], v[34:35] neg_lo:[1,0,0] neg_hi:[1,0,0]
	v_pk_fma_f32 v[38:39], v[126:127], v[46:47], v[38:39] neg_lo:[1,0,0] neg_hi:[1,0,0]
	ds_read_b128 v[44:47], v174 offset:7680
	v_cndmask_b32_e64 v132, 0, 1.0, vcc
	v_mov_b32_e32 v133, 0
	v_mov_b64_e32 v[144:145], 0
	s_waitcnt lgkmcnt(6)
	v_pk_fma_f32 v[34:35], v[128:129], v[48:49], v[34:35] neg_lo:[1,0,0] neg_hi:[1,0,0]
	v_pk_fma_f32 v[38:39], v[130:131], v[50:51], v[38:39] neg_lo:[1,0,0] neg_hi:[1,0,0]
	ds_read_b128 v[48:51], v174 offset:7696
	s_waitcnt lgkmcnt(6)
	v_pk_fma_f32 v[34:35], v[150:151], v[52:53], v[34:35] neg_lo:[1,0,0] neg_hi:[1,0,0]
	v_pk_fma_f32 v[38:39], v[152:153], v[54:55], v[38:39] neg_lo:[1,0,0] neg_hi:[1,0,0]
	ds_read_b128 v[52:55], v174 offset:7712
	s_waitcnt lgkmcnt(6)
	v_pk_fma_f32 v[34:35], v[206:207], v[56:57], v[34:35] neg_lo:[1,0,0] neg_hi:[1,0,0]
	v_pk_fma_f32 v[38:39], v[208:209], v[58:59], v[38:39] neg_lo:[1,0,0] neg_hi:[1,0,0]
	ds_read_b128 v[56:59], v174 offset:7728
	s_waitcnt lgkmcnt(6)
	v_pk_fma_f32 v[34:35], v[210:211], v[62:63], v[34:35] neg_lo:[1,0,0] neg_hi:[1,0,0]
	v_pk_fma_f32 v[38:39], v[212:213], v[64:65], v[38:39] neg_lo:[1,0,0] neg_hi:[1,0,0]
	ds_read_b128 v[62:65], v174 offset:7744
	s_waitcnt lgkmcnt(6)
	v_pk_fma_f32 v[34:35], v[214:215], v[114:115], v[34:35] neg_lo:[1,0,0] neg_hi:[1,0,0]
	v_pk_fma_f32 v[38:39], v[216:217], v[116:117], v[38:39] neg_lo:[1,0,0] neg_hi:[1,0,0]
	ds_read_b128 v[114:117], v174 offset:7760
	s_waitcnt lgkmcnt(6)
	v_pk_fma_f32 v[34:35], v[218:219], v[118:119], v[34:35] neg_lo:[1,0,0] neg_hi:[1,0,0]
	v_pk_fma_f32 v[38:39], v[220:221], v[120:121], v[38:39] neg_lo:[1,0,0] neg_hi:[1,0,0]
	ds_read_b128 v[118:121], v174 offset:7776
	s_waitcnt lgkmcnt(14)
	v_pk_fma_f32 v[34:35], v[146:147], v[138:139], v[34:35] neg_lo:[1,0,0] neg_hi:[1,0,0]
	v_pk_fma_f32 v[38:39], v[172:173], v[140:141], v[38:39] neg_lo:[1,0,0] neg_hi:[1,0,0]
	ds_read_b128 v[138:141], v174 offset:7792
	v_add_f32_e32 v122, v34, v35
	v_add_f32_e32 v123, v38, v39
	v_add_f32_e32 v147, v122, v123
	v_cmp_eq_u32_e32 vcc, 31, v33
	s_waitcnt lgkmcnt(7)
	v_pk_fma_f32 v[132:133], v[124:125], v[44:45], v[132:133] neg_lo:[1,0,0] neg_hi:[1,0,0]
	v_pk_fma_f32 v[144:145], v[126:127], v[46:47], v[144:145] neg_lo:[1,0,0] neg_hi:[1,0,0]
	ds_read_b128 v[44:47], v174 offset:7936
	v_cndmask_b32_e64 v34, 0, 1.0, vcc
	v_mov_b32_e32 v35, 0
	v_mov_b64_e32 v[38:39], 0
	s_waitcnt lgkmcnt(7)
	v_pk_fma_f32 v[132:133], v[128:129], v[48:49], v[132:133] neg_lo:[1,0,0] neg_hi:[1,0,0]
	v_pk_fma_f32 v[144:145], v[130:131], v[50:51], v[144:145] neg_lo:[1,0,0] neg_hi:[1,0,0]
	ds_read_b128 v[48:51], v174 offset:7952
	s_waitcnt lgkmcnt(7)
	v_pk_fma_f32 v[132:133], v[150:151], v[52:53], v[132:133] neg_lo:[1,0,0] neg_hi:[1,0,0]
	v_pk_fma_f32 v[144:145], v[152:153], v[54:55], v[144:145] neg_lo:[1,0,0] neg_hi:[1,0,0]
	ds_read_b128 v[52:55], v174 offset:7968
	s_waitcnt lgkmcnt(7)
	v_pk_fma_f32 v[132:133], v[206:207], v[56:57], v[132:133] neg_lo:[1,0,0] neg_hi:[1,0,0]
	v_pk_fma_f32 v[144:145], v[208:209], v[58:59], v[144:145] neg_lo:[1,0,0] neg_hi:[1,0,0]
	ds_read_b128 v[56:59], v174 offset:7984
	s_waitcnt lgkmcnt(7)
	v_pk_fma_f32 v[132:133], v[210:211], v[62:63], v[132:133] neg_lo:[1,0,0] neg_hi:[1,0,0]
	v_pk_fma_f32 v[144:145], v[212:213], v[64:65], v[144:145] neg_lo:[1,0,0] neg_hi:[1,0,0]
	ds_read_b128 v[62:65], v174 offset:8000
	s_waitcnt lgkmcnt(7)
; #define LAS __attribute__((address_space(3)))
; DI unsigned f2bf(float f) { unsigned u = __float_as_uint(f); u += 0x7FFFu + ((u >> 16) & 1u); return u >> 16; }
; DI void gdn_unit(const Params& P, bf16_t* proj, const float* gb, int b, int h, LAS unsigned char* lds) {
;     ...
; #pragma unroll
;             for (int i = 0; i < 32; ++i) {
;                 float s0 = (cl == i) ? 1.0f : 0.0f, s1 = 0.f, s2 = 0.f, s3 = 0.f;
;                 f32x4 lr[8];
; #pragma unroll
;                 for (int j4 = 0; j4 < (i + 3) / 4; ++j4) lr[j4] = *(const LAS f32x4*)(Lblk + i * 64 + j4 * 4);
;                 __builtin_amdgcn_sched_barrier(0);
; #pragma unroll
;                 for (int j4 = 0; j4 < (i + 3) / 4; ++j4) {
;                     const f32x4 l4 = lr[j4];
;                     if (j4 * 4 + 0 < i) s0 -= l4[0] * Tc[j4 * 4 + 0];
;                     if (j4 * 4 + 1 < i) s1 -= l4[1] * Tc[j4 * 4 + 1];
;                     if (j4 * 4 + 2 < i) s2 -= l4[2] * Tc[j4 * 4 + 2];
;                     if (j4 * 4 + 3 < i) s3 -= l4[3] * Tc[j4 * 4 + 3];
;                 }
;                 Tc[i] = (s0 + s1) + (s2 + s3);
;             }
;             const float sc1 = beta * egc, sc2 = beta;
; #pragma unroll
;             for (int i = 0; i < 32; ++i) {
;                 const int row = blk * 32 + i;
;                 *(LAS bf16_t*)(lds + TP_OFF + row * 144 + lane * 2) = (bf16_t)f2bf(Tc[i] * sc1);
;                 *(LAS bf16_t*)(lds + TPP_OFF + row * 144 + lane * 2) = (bf16_t)f2bf(Tc[i] * sc2);
;             }
	v_pk_fma_f32 v[132:133], v[214:215], v[114:115], v[132:133] neg_lo:[1,0,0] neg_hi:[1,0,0]
	v_pk_fma_f32 v[144:145], v[216:217], v[116:117], v[144:145] neg_lo:[1,0,0] neg_hi:[1,0,0]
	ds_read_b128 v[114:117], v174 offset:8016
	s_waitcnt lgkmcnt(7)
	v_pk_fma_f32 v[132:133], v[218:219], v[118:119], v[132:133] neg_lo:[1,0,0] neg_hi:[1,0,0]
	v_pk_fma_f32 v[144:145], v[220:221], v[120:121], v[144:145] neg_lo:[1,0,0] neg_hi:[1,0,0]
	ds_read_b128 v[118:121], v174 offset:8032
	s_waitcnt lgkmcnt(7)
	v_pk_fma_f32 v[132:133], v[146:147], v[138:139], v[132:133] neg_lo:[1,0,0] neg_hi:[1,0,0]
	v_pk_fma_f32 v[144:145], v[172:173], v[140:141], v[144:145] neg_lo:[1,0,0] neg_hi:[1,0,0]
	ds_read_b128 v[138:141], v174 offset:8048
	v_add_f32_e32 v122, v132, v133
	v_add_f32_e32 v123, v144, v145
	v_add_f32_e32 v172, v122, v123
	s_waitcnt lgkmcnt(7)
	v_pk_fma_f32 v[34:35], v[124:125], v[44:45], v[34:35] neg_lo:[1,0,0] neg_hi:[1,0,0]
	v_pk_fma_f32 v[38:39], v[126:127], v[46:47], v[38:39] neg_lo:[1,0,0] neg_hi:[1,0,0]
	s_waitcnt lgkmcnt(6)
	v_pk_fma_f32 v[34:35], v[128:129], v[48:49], v[34:35] neg_lo:[1,0,0] neg_hi:[1,0,0]
	v_pk_fma_f32 v[38:39], v[130:131], v[50:51], v[38:39] neg_lo:[1,0,0] neg_hi:[1,0,0]
	s_waitcnt lgkmcnt(5)
	v_pk_fma_f32 v[34:35], v[150:151], v[52:53], v[34:35] neg_lo:[1,0,0] neg_hi:[1,0,0]
	v_pk_fma_f32 v[38:39], v[152:153], v[54:55], v[38:39] neg_lo:[1,0,0] neg_hi:[1,0,0]
	s_waitcnt lgkmcnt(4)
	v_pk_fma_f32 v[34:35], v[206:207], v[56:57], v[34:35] neg_lo:[1,0,0] neg_hi:[1,0,0]
	v_pk_fma_f32 v[38:39], v[208:209], v[58:59], v[38:39] neg_lo:[1,0,0] neg_hi:[1,0,0]
	s_waitcnt lgkmcnt(3)
	v_pk_fma_f32 v[34:35], v[210:211], v[62:63], v[34:35] neg_lo:[1,0,0] neg_hi:[1,0,0]
	v_pk_fma_f32 v[38:39], v[212:213], v[64:65], v[38:39] neg_lo:[1,0,0] neg_hi:[1,0,0]
	s_waitcnt lgkmcnt(2)
	v_pk_fma_f32 v[34:35], v[214:215], v[114:115], v[34:35] neg_lo:[1,0,0] neg_hi:[1,0,0]
	v_pk_fma_f32 v[38:39], v[216:217], v[116:117], v[38:39] neg_lo:[1,0,0] neg_hi:[1,0,0]
	s_waitcnt lgkmcnt(1)
	v_pk_fma_f32 v[34:35], v[218:219], v[118:119], v[34:35] neg_lo:[1,0,0] neg_hi:[1,0,0]
	v_pk_fma_f32 v[38:39], v[220:221], v[120:121], v[38:39] neg_lo:[1,0,0] neg_hi:[1,0,0]
	s_waitcnt lgkmcnt(0)
	v_pk_fma_f32 v[34:35], v[146:147], v[138:139], v[34:35] neg_lo:[1,0,0] neg_hi:[1,0,0]
	v_pk_fma_f32 v[38:39], v[172:173], v[140:141], v[38:39] neg_lo:[1,0,0] neg_hi:[1,0,0]
	v_add_f32_e32 v122, v34, v35
	v_add_f32_e32 v123, v38, v39
	v_add_f32_e32 v173, v122, v123
	v_mov_b32_e32 v37, v124
	v_mov_b32_e32 v32, v125
	v_mov_b32_e32 v34, v126
	v_mov_b32_e32 v35, v127
	v_mov_b32_e32 v39, v128
	v_mov_b32_e32 v38, v129
	v_mov_b32_e32 v43, v130
	v_mov_b32_e32 v44, v131
	v_mov_b32_e32 v45, v150
	v_mov_b32_e32 v47, v151
	v_mov_b32_e32 v46, v152
	v_mov_b32_e32 v48, v153
	v_mov_b32_e32 v50, v206
	v_mov_b32_e32 v52, v207
	v_mov_b32_e32 v51, v208
	v_mov_b32_e32 v53, v209
	v_mov_b32_e32 v54, v210
	v_mov_b32_e32 v56, v211
	v_mov_b32_e32 v55, v212
	v_mov_b32_e32 v57, v213
	v_mov_b32_e32 v58, v214
	v_mov_b32_e32 v62, v215
	v_mov_b32_e32 v59, v216
	v_mov_b32_e32 v63, v217
	v_mov_b32_e32 v64, v218
	v_mov_b32_e32 v114, v219
	v_mov_b32_e32 v65, v220
	v_mov_b32_e32 v115, v221
	v_mov_b32_e32 v49, v146
	v_mov_b32_e32 v117, v147
	v_mov_b32_e32 v116, v172
	v_mov_b32_e32 v118, v173
	v_mul_f32_e32 v119, v108, v109
	v_and_b32_e32 v120, 0xfffffe0, v67
	v_readlane_b32 s0, v255, 9
	v_mul_f32_e32 v121, v37, v119
	v_bfe_u32 v122, v121, 16, 1
	v_add_u32_e32 v109, s0, v60
	v_mul_lo_u32 v120, v120, s37
	v_add3_u32 v121, v121, v122, s68
	v_add_u32_e32 v122, v109, v120
	v_readlane_b32 s0, v255, 10
	ds_write_b16_d16_hi v122, v121
	v_mul_f32_e32 v121, v108, v37
	v_add_u32_e32 v60, s0, v60
	v_bfe_u32 v123, v121, 16, 1
	v_add3_u32 v121, v121, v123, s68
	v_add_u32_e32 v120, v60, v120
	ds_write_b16_d16_hi v120, v121
	v_mul_f32_e32 v121, v119, v32
	v_mul_f32_e32 v123, v108, v32
	v_cvt_pk_bf16_f32 v121, v121, v123
	ds_write_b16 v122, v121 offset:144
	ds_write_b16_d16_hi v120, v121 offset:144
	v_mul_f32_e32 v172, v119, v34
	v_mul_f32_e32 v173, v108, v34
	v_cvt_pk_bf16_f32 v172, v172, v173
	ds_write_b16 v122, v172 offset:288
	ds_write_b16_d16_hi v120, v172 offset:288
	v_mul_f32_e32 v121, v119, v35
	v_mul_f32_e32 v123, v108, v35
	v_cvt_pk_bf16_f32 v121, v121, v123
	ds_write_b16 v122, v121 offset:432
	ds_write_b16_d16_hi v120, v121 offset:432
	v_mul_f32_e32 v172, v119, v39
	v_mul_f32_e32 v173, v108, v39
	v_cvt_pk_bf16_f32 v172, v172, v173
	ds_write_b16 v122, v172 offset:576
	ds_write_b16_d16_hi v120, v172 offset:576
	v_mul_f32_e32 v121, v119, v38
	v_mul_f32_e32 v123, v108, v38
	v_cvt_pk_bf16_f32 v121, v121, v123
	ds_write_b16 v122, v121 offset:720
	ds_write_b16_d16_hi v120, v121 offset:720
	v_mul_f32_e32 v172, v119, v43
	v_mul_f32_e32 v173, v108, v43
	v_cvt_pk_bf16_f32 v172, v172, v173
	ds_write_b16 v122, v172 offset:864
	ds_write_b16_d16_hi v120, v172 offset:864
	v_mul_f32_e32 v121, v119, v44
	v_mul_f32_e32 v123, v108, v44
	v_cvt_pk_bf16_f32 v121, v121, v123
	ds_write_b16 v122, v121 offset:1008
	ds_write_b16_d16_hi v120, v121 offset:1008
	v_mul_f32_e32 v172, v119, v45
	v_mul_f32_e32 v173, v108, v45
	v_cvt_pk_bf16_f32 v172, v172, v173
	ds_write_b16 v122, v172 offset:1152
; #define LAS __attribute__((address_space(3)))
; DI unsigned f2bf(float f) { unsigned u = __float_as_uint(f); u += 0x7FFFu + ((u >> 16) & 1u); return u >> 16; }
; DI void gdn_unit(const Params& P, bf16_t* proj, const float* gb, int b, int h, LAS unsigned char* lds) {
;     ...
;             const float sc1 = beta * egc, sc2 = beta;
; #pragma unroll
;             for (int i = 0; i < 32; ++i) {
;                 const int row = blk * 32 + i;
;                 *(LAS bf16_t*)(lds + TP_OFF + row * 144 + lane * 2) = (bf16_t)f2bf(Tc[i] * sc1);
;                 *(LAS bf16_t*)(lds + TPP_OFF + row * 144 + lane * 2) = (bf16_t)f2bf(Tc[i] * sc2);
;             }
;             if (blk == 1) {
; #pragma unroll
;                 for (int i = 0; i < 32; ++i) { *(LAS bf16_t*)(lds + TP_OFF + i * 144 + lane * 2) = (bf16_t)0; *(LAS bf16_t*)(lds + TPP_OFF + i * 144 + lane * 2) = (bf16_t)0; }
;             }
	ds_write_b16_d16_hi v120, v172 offset:1152
	v_mul_f32_e32 v121, v119, v47
	v_mul_f32_e32 v123, v108, v47
	v_cvt_pk_bf16_f32 v121, v121, v123
	ds_write_b16 v122, v121 offset:1296
	ds_write_b16_d16_hi v120, v121 offset:1296
	v_mul_f32_e32 v172, v119, v46
	v_mul_f32_e32 v173, v108, v46
	v_cvt_pk_bf16_f32 v172, v172, v173
	ds_write_b16 v122, v172 offset:1440
	ds_write_b16_d16_hi v120, v172 offset:1440
	v_mul_f32_e32 v121, v119, v48
	v_mul_f32_e32 v123, v108, v48
	v_cvt_pk_bf16_f32 v121, v121, v123
	ds_write_b16 v122, v121 offset:1584
	ds_write_b16_d16_hi v120, v121 offset:1584
	v_mul_f32_e32 v172, v119, v50
	v_mul_f32_e32 v173, v108, v50
	v_cvt_pk_bf16_f32 v172, v172, v173
	ds_write_b16 v122, v172 offset:1728
	ds_write_b16_d16_hi v120, v172 offset:1728
	v_mul_f32_e32 v121, v119, v52
	v_mul_f32_e32 v123, v108, v52
	v_cvt_pk_bf16_f32 v121, v121, v123
	ds_write_b16 v122, v121 offset:1872
	ds_write_b16_d16_hi v120, v121 offset:1872
	v_mul_f32_e32 v172, v119, v51
	v_mul_f32_e32 v173, v108, v51
	v_cvt_pk_bf16_f32 v172, v172, v173
	ds_write_b16 v122, v172 offset:2016
	ds_write_b16_d16_hi v120, v172 offset:2016
	v_mul_f32_e32 v121, v119, v53
	v_mul_f32_e32 v123, v108, v53
	v_cvt_pk_bf16_f32 v121, v121, v123
	ds_write_b16 v122, v121 offset:2160
	ds_write_b16_d16_hi v120, v121 offset:2160
	v_mul_f32_e32 v172, v119, v54
	v_mul_f32_e32 v173, v108, v54
	v_cvt_pk_bf16_f32 v172, v172, v173
	ds_write_b16 v122, v172 offset:2304
	ds_write_b16_d16_hi v120, v172 offset:2304
	v_mul_f32_e32 v121, v119, v56
	v_mul_f32_e32 v123, v108, v56
	v_cvt_pk_bf16_f32 v121, v121, v123
	ds_write_b16 v122, v121 offset:2448
	ds_write_b16_d16_hi v120, v121 offset:2448
	v_mul_f32_e32 v172, v119, v55
	v_mul_f32_e32 v173, v108, v55
	v_cvt_pk_bf16_f32 v172, v172, v173
	ds_write_b16 v122, v172 offset:2592
	ds_write_b16_d16_hi v120, v172 offset:2592
	v_mul_f32_e32 v121, v119, v57
	v_mul_f32_e32 v123, v108, v57
	v_cvt_pk_bf16_f32 v121, v121, v123
	ds_write_b16 v122, v121 offset:2736
	ds_write_b16_d16_hi v120, v121 offset:2736
	v_mul_f32_e32 v172, v119, v58
	v_mul_f32_e32 v173, v108, v58
	v_cvt_pk_bf16_f32 v172, v172, v173
	ds_write_b16 v122, v172 offset:2880
	ds_write_b16_d16_hi v120, v172 offset:2880
	v_mul_f32_e32 v121, v119, v62
	v_mul_f32_e32 v123, v108, v62
	v_cvt_pk_bf16_f32 v121, v121, v123
	ds_write_b16 v122, v121 offset:3024
	ds_write_b16_d16_hi v120, v121 offset:3024
	v_mul_f32_e32 v172, v119, v59
	v_mul_f32_e32 v173, v108, v59
	v_cvt_pk_bf16_f32 v172, v172, v173
	ds_write_b16 v122, v172 offset:3168
	ds_write_b16_d16_hi v120, v172 offset:3168
	v_mul_f32_e32 v121, v119, v63
	v_mul_f32_e32 v123, v108, v63
	v_cvt_pk_bf16_f32 v121, v121, v123
	ds_write_b16 v122, v121 offset:3312
	ds_write_b16_d16_hi v120, v121 offset:3312
	v_mul_f32_e32 v172, v119, v64
	v_mul_f32_e32 v173, v108, v64
	v_cvt_pk_bf16_f32 v172, v172, v173
	ds_write_b16 v122, v172 offset:3456
	ds_write_b16_d16_hi v120, v172 offset:3456
	v_mul_f32_e32 v121, v119, v114
	v_mul_f32_e32 v123, v108, v114
	v_cvt_pk_bf16_f32 v121, v121, v123
	ds_write_b16 v122, v121 offset:3600
	ds_write_b16_d16_hi v120, v121 offset:3600
	v_mul_f32_e32 v172, v119, v65
	v_mul_f32_e32 v173, v108, v65
	v_cvt_pk_bf16_f32 v172, v172, v173
	ds_write_b16 v122, v172 offset:3744
	ds_write_b16_d16_hi v120, v172 offset:3744
	v_mul_f32_e32 v121, v119, v115
	v_mul_f32_e32 v123, v108, v115
	v_cvt_pk_bf16_f32 v121, v121, v123
	ds_write_b16 v122, v121 offset:3888
	ds_write_b16_d16_hi v120, v121 offset:3888
	v_mul_f32_e32 v172, v119, v49
	v_mul_f32_e32 v173, v108, v49
	v_cvt_pk_bf16_f32 v172, v172, v173
	ds_write_b16 v122, v172 offset:4032
	ds_write_b16_d16_hi v120, v172 offset:4032
	v_mul_f32_e32 v121, v119, v117
	v_mul_f32_e32 v123, v108, v117
	v_cvt_pk_bf16_f32 v121, v121, v123
	ds_write_b16 v122, v121 offset:4176
	ds_write_b16_d16_hi v120, v121 offset:4176
	v_mul_f32_e32 v121, v119, v116
	v_bfe_u32 v123, v121, 16, 1
	v_add3_u32 v121, v121, v123, s68
	ds_write_b16_d16_hi v122, v121 offset:4320
	v_mul_f32_e32 v121, v108, v116
	v_bfe_u32 v122, v121, 16, 1
	v_add3_u32 v121, v121, v122, s68
	ds_write_b16_d16_hi v120, v121 offset:4320
	v_or_b32_e32 v120, 31, v67
	v_mul_f32_e32 v119, v119, v118
	v_bfe_u32 v121, v119, 16, 1
	v_mul_lo_u32 v120, v120, s37
	v_add3_u32 v119, v119, v121, s68
	v_add_u32_e32 v121, v109, v120
	v_mul_f32_e32 v108, v108, v118
	ds_write_b16_d16_hi v121, v119
	v_bfe_u32 v119, v108, 16, 1
	v_add3_u32 v108, v108, v119, s68
	v_add_u32_e32 v119, v60, v120
	v_cmp_eq_u32_e32 vcc, 1, v36
	ds_write_b16_d16_hi v119, v108
	s_and_saveexec_b64 s[0:1], vcc
	s_cbranch_execz .LBB0_494
	v_lshlrev_b32_e32 v121, 1, v33
	v_lshrrev_b32_e32 v123, 2, v33
	v_mul_u32_u24_e32 v123, 0x90, v123
	v_sub_u32_e32 v123, v123, v121
	v_and_b32_e32 v121, 3, v33
	v_lshl_add_u32 v123, v121, 4, v123
	v_add_u32_e32 v121, v109, v123
	v_add_u32_e32 v123, v60, v123
	v_mov_b64_e32 v[172:173], 0
	v_mov_b64_e32 v[174:175], 0
	ds_write_b128 v121, v[172:175]
	ds_write_b128 v123, v[172:175]
	ds_write_b128 v121, v[172:175] offset:1152
	ds_write_b128 v123, v[172:175] offset:1152
	ds_write_b128 v121, v[172:175] offset:2304
	ds_write_b128 v123, v[172:175] offset:2304
	ds_write_b128 v121, v[172:175] offset:3456
	ds_write_b128 v123, v[172:175] offset:3456
